# hyena: odd tap copy 64B further in LDS (bank offset) on top of v41
# speedup vs baseline: 1.0041x; 1.0041x over previous
; #define LAS __attribute__((address_space(3)))
; DI float wave_sum(float v) {
; #pragma unroll
;     for (int o = 1; o < 64; o <<= 1) v += __shfl_xor(v, o);
;     return v;
; DI void hyena_unit(const Inputs& in, int l, unsigned char* ws, int half, int c, LAS unsigned char* lds, int tid) {
;     const int L = half ? 2048 : 4096, NB = half ? 8 : 4, nblk = L / 32, FRS = half ? FRS1 : FRS0, ZS = L + 2048, ZSP = (ZS / 32) * 40;
;     const bf16_t* FR = (const bf16_t*)(ws + (half ? WS_FR1 : WS_FR0)) + (size_t)c * FRS; const bf16_t* FRO = (const bf16_t*)(ws + (half ? WS_FRO1 : WS_FRO0)) + (size_t)c * FRS;
;     const bf16_t* ZT = (const bf16_t*)(ws + WS_ZT); bf16_t* XT = (bf16_t*)(ws + WS_X0T);
;     constexpr int FRB = 16640;
;     LAS unsigned char* Zl = lds + 2 * FRB;
.LBB0_105:
	v_and_b32_e32 v0, 64, v249
	v_add_u32_e32 v0, 64, v0
	v_xor_b32_e32 v1, 1, v249
	v_cmp_lt_i32_e32 vcc, v1, v0
	s_add_i32 s0, 0, 0x23fc0
	v_writelane_b32 v255, s0, 4
	v_cndmask_b32_e32 v1, v249, v1, vcc
	v_lshlrev_b32_e32 v206, 2, v1
	v_xor_b32_e32 v1, 2, v249
	v_cmp_lt_i32_e32 vcc, v1, v0
	s_add_i32 s0, 0, 0x23fc4
	v_writelane_b32 v255, s0, 5
	v_cndmask_b32_e32 v1, v249, v1, vcc
	v_lshlrev_b32_e32 v207, 2, v1
	v_xor_b32_e32 v1, 4, v249
	v_cmp_lt_i32_e32 vcc, v1, v0
	s_add_i32 s2, 0, 0x8c30
	v_writelane_b32 v255, s2, 6
	v_cndmask_b32_e32 v1, v249, v1, vcc
	v_lshlrev_b32_e32 v208, 2, v1
	v_xor_b32_e32 v1, 8, v249
	v_cmp_lt_i32_e32 vcc, v1, v0
	s_add_i32 s2, 0, 0x19800
	v_writelane_b32 v255, s2, 7
	v_cndmask_b32_e32 v1, v249, v1, vcc
	v_lshlrev_b32_e32 v209, 2, v1
	v_xor_b32_e32 v1, 16, v249
	v_cmp_lt_i32_e32 vcc, v1, v0
	v_writelane_b32 v255, s83, 8
	v_writelane_b32 v255, s84, 9
	v_cndmask_b32_e32 v1, v249, v1, vcc
	v_lshlrev_b32_e32 v210, 2, v1
	v_xor_b32_e32 v1, 32, v249
	v_cmp_lt_i32_e32 vcc, v1, v0
	v_mov_b32_e32 v177, 0
	v_writelane_b32 v255, s85, 10
	v_cndmask_b32_e32 v0, v249, v1, vcc
	v_lshlrev_b32_e32 v211, 2, v0
	v_lshlrev_b32_e32 v0, 2, v249
	s_mov_b32 s75, 1
	v_and_b32_e32 v212, 0x100, v0
	s_mov_b64 s[66:67], 0x200000
	s_mov_b64 s[68:69], 0x80
	s_mov_b32 s70, 0x437f0000
	s_mov_b64 s[72:73], 0x2400
	v_mov_b32_e32 v216, 1
	v_mov_b32_e32 v217, 0x358637bd
	v_mov_b32_e32 v218, 0x3ecc95a3
	s_movk_i32 s0, 0x78
	s_movk_i32 s1, 0x88
	s_mov_b32 s76, 0x3db504f3
	s_add_i32 s82, 0, 0x11000
	s_mov_b32 s43, 0x42b504f3
	s_mov_b32 s78, 0x3e0293ee
	s_mov_b32 s80, 0x3b808081
	v_mov_b32_e32 v221, 0x7f800000
	v_mov_b32_e32 v222, 0x7fc00000
	v_mov_b32_e32 v223, 0xff800000
	v_mov_b32_e32 v224, 0x2200
	v_mov_b32_e32 v225, 0x880
	v_mov_b32_e32 v220, 0x1100
	v_mov_b32_e32 v254, 0x2a80
	v_mov_b32_e32 v219, 0x3300
	v_mov_b32_e32 v214, v177
	v_mov_b32_e32 v215, v177
	s_mov_b32 s79, 0
	s_mov_b32 s45, 0
	v_writelane_b32 v255, s81, 11
	s_branch .LBB0_109

; #define LAS __attribute__((address_space(3)))
; DI void hyena_unit(const Inputs& in, int l, unsigned char* ws, int half, int c, LAS unsigned char* lds, int tid) {
;     const int L = half ? 2048 : 4096, NB = half ? 8 : 4, nblk = L / 32, FRS = half ? FRS1 : FRS0, ZS = L + 2048, ZSP = (ZS / 32) * 40;
;     const bf16_t* FR = (const bf16_t*)(ws + (half ? WS_FR1 : WS_FR0)) + (size_t)c * FRS; const bf16_t* FRO = (const bf16_t*)(ws + (half ? WS_FRO1 : WS_FRO0)) + (size_t)c * FRS;
;     const bf16_t* ZT = (const bf16_t*)(ws + WS_ZT); bf16_t* XT = (bf16_t*)(ws + WS_X0T);
;     constexpr int FRB = 16640;
;     LAS unsigned char* Zl = lds + 2 * FRB;
;     const int cpr = ZS / 8, nfr = (2 * L + 64) / 8;
;     { u32x4 fv[5], zv[8];
; #pragma unroll
;       for (int k = 0; k < 5; ++k) { const int i = tid + 512 * k, cp = i >= nfr, kk = cp ? i - nfr : i; fv[k] = (u32x4){0u, 0u, 0u, 0u};
;           if (i < 2 * nfr && kk < 2 * L / 8) fv[k] = *(const u32x4*)((cp ? FRO : FR) + kk * 8);
;           if (cp && kk == 2 * L / 8 - 1) fv[k].w &= 0xffffu; }
; #pragma unroll
;       for (int k = 0; k < 8; ++k) { const int i = tid + 512 * k, b = i / cpr, j = i % cpr, m = j * 8 - 1024; zv[k] = (u32x4){0u, 0u, 0u, 0u};
;           if (i < NB * cpr && m >= 0 && m < L) zv[k] = *(const u32x4*)(ZT + (size_t)(b * 512 + c) * L + m); }
; #pragma unroll
;       for (int k = 0; k < 5; ++k) { const int i = tid + 512 * k, cp = i >= nfr, kk = cp ? i - nfr : i; if (i < 2 * nfr) *(LAS u32x4*)(lds + cp * FRB + kk * 16) = fv[k]; }
; #pragma unroll
;       for (int k = 0; k < 8; ++k) { const int i = tid + 512 * k, b = i / cpr, j = i % cpr; if (i < NB * cpr) *(LAS u32x4*)(Zl + ((size_t)b * ZSP + (j >> 2) * 40 + (j & 3) * 8) * 2) = zv[k]; } }
.LBB0_615:
	s_cmpk_gt_i32 s79, 0x1ff
	s_cbranch_scc1 .LBB0_674
	s_and_b64 s[2:3], s[90:91], exec
	s_movk_i32 s2, 0x2040
	s_cselect_b32 s44, s2, 0x1040
	s_add_i32 s22, s81, 0x800
	s_lshr_b32 s83, s22, 5
	s_and_b64 s[2:3], s[90:91], exec
	s_mov_b32 s2, 0xc10000
	s_cselect_b32 s6, 0x400000, s2
	s_mov_b32 s2, 0x1dd00000
	s_cselect_b32 s7, s2, 0x1e510000
	s_lshr_b32 s20, s81, 2
	s_or_b32 s42, s20, 8
	v_mov_b32_e32 v0, s42
	v_cmp_le_i32_e32 vcc, s42, v182
	s_lshl_b32 s18, s42, 1
	s_add_i32 s23, s20, -1
	v_cndmask_b32_e32 v1, 0, v0, vcc
	v_sub_u32_e32 v2, v182, v1
	v_cmp_gt_i32_e64 s[2:3], s18, v182
	v_cmp_gt_i32_e64 s[4:5], s20, v2
	s_and_b64 s[46:47], s[2:3], s[4:5]
	v_mov_b32_e32 v1, s6
	v_mov_b32_e32 v3, s7
	v_cmp_eq_u32_e64 s[4:5], s23, v2
	v_add_u32_e32 v4, 0x200, v182
	v_cndmask_b32_e32 v176, v1, v3, vcc
	s_and_b64 s[4:5], vcc, s[4:5]
	v_cmp_le_i32_e32 vcc, s42, v4
	v_cmp_gt_i32_e64 s[6:7], s18, v4
	v_add_u32_e32 v6, 0x400, v182
	v_cndmask_b32_e32 v5, 0, v0, vcc
	v_sub_u32_e32 v5, v4, v5
	v_cmp_gt_i32_e64 s[8:9], s20, v5
	s_and_b64 s[48:49], s[6:7], s[8:9]
	v_cmp_eq_u32_e64 s[8:9], s23, v5
	v_cndmask_b32_e32 v54, v1, v3, vcc
	s_and_b64 s[8:9], vcc, s[8:9]
	v_cmp_le_i32_e32 vcc, s42, v6
	v_cmp_gt_i32_e64 s[10:11], s18, v6
	v_add_u32_e32 v8, 0x600, v182
	v_cndmask_b32_e32 v7, 0, v0, vcc
	v_sub_u32_e32 v7, v6, v7
	v_cmp_gt_i32_e64 s[12:13], s20, v7
	s_and_b64 s[50:51], s[10:11], s[12:13]
	v_cmp_eq_u32_e64 s[12:13], s23, v7
	v_cndmask_b32_e32 v58, v1, v3, vcc
	s_and_b64 s[12:13], vcc, s[12:13]
	v_cmp_le_i32_e32 vcc, s42, v8
	v_cmp_gt_i32_e64 s[14:15], s18, v8
	v_add_u32_e32 v10, 0x800, v182
	v_cndmask_b32_e32 v9, 0, v0, vcc
	v_sub_u32_e32 v9, v8, v9
	v_cmp_gt_i32_e64 s[16:17], s20, v9
	s_and_b64 s[52:53], s[14:15], s[16:17]
	v_cmp_eq_u32_e64 s[16:17], s23, v9
	v_cndmask_b32_e32 v62, v1, v3, vcc
	s_and_b64 s[16:17], vcc, s[16:17]
	v_cmp_le_i32_e32 vcc, s42, v10
	v_cmp_gt_i32_e64 s[18:19], s18, v10
	s_lshr_b32 s89, s81, 5
	v_cndmask_b32_e32 v0, 0, v0, vcc
	v_sub_u32_e32 v11, v10, v0
	v_cmp_gt_i32_e64 s[20:21], s20, v11
	s_and_b64 s[54:55], s[18:19], s[20:21]
	v_cmp_eq_u32_e64 s[20:21], s23, v11
	s_and_b64 s[20:21], vcc, s[20:21]
	s_waitcnt lgkmcnt(0)
	s_add_u32 s74, s92, 0x1bd00000
	s_addc_u32 s75, s93, 0
	s_lshr_b32 s40, s22, 3
	v_cvt_f32_u32_e32 v0, s40
	s_and_b64 s[22:23], s[90:91], exec
	s_cselect_b32 s22, 2, 3
	s_lshl_b32 s41, s40, s22
	v_rcp_iflag_f32_e32 v0, v0
	s_and_b64 s[22:23], s[90:91], exec
	s_cselect_b32 s33, 12, 11
	s_sub_i32 s22, 0, s40
	v_mul_f32_e32 v0, 0x4f7ffffe, v0
	v_cvt_u32_f32_e32 v0, v0
	v_cndmask_b32_e32 v66, v1, v3, vcc
	v_sub_u32_e32 v1, 0, v182
	v_max_i32_e32 v1, v182, v1
	v_mul_lo_u32 v3, s22, v0
	v_mul_hi_u32 v3, v0, v3
	v_add_u32_e32 v3, v0, v3
	v_mul_hi_u32 v0, v1, v3
	v_mul_lo_u32 v12, v0, s40
	v_sub_u32_e32 v1, v1, v12
	v_add_u32_e32 v12, 1, v0
	v_cmp_le_u32_e32 vcc, s40, v1
	v_ashrrev_i32_e32 v22, 31, v182
	v_cmp_gt_i32_e64 s[22:23], s41, v182
	v_cndmask_b32_e32 v0, v0, v12, vcc
	v_subrev_u32_e32 v12, s40, v1
	v_cndmask_b32_e32 v1, v1, v12, vcc
	v_add_u32_e32 v12, 1, v0
	v_cmp_le_u32_e32 vcc, s40, v1
	v_mov_b32_e32 v1, v177
	s_movk_i32 s86, 0x7f
	v_cndmask_b32_e32 v0, v0, v12, vcc
	v_xor_b32_e32 v0, v0, v22
	v_sub_u32_e32 v23, v0, v22
	v_mul_lo_u32 v0, v23, s40
	v_sub_u32_e32 v12, v182, v0
	v_lshlrev_b32_e32 v13, 3, v12
	v_add_u32_e32 v0, 0xfffffc00, v13
	v_lshl_add_u64 v[70:71], v[0:1], 1, s[74:75]
	v_sub_u32_e32 v1, 0, v4
	v_max_i32_e32 v1, v4, v1
	v_mul_hi_u32 v14, v1, v3
	v_cmp_gt_i32_e64 s[24:25], s81, v0
	v_mul_lo_u32 v15, v14, s40
	v_cmp_lt_i32_e32 vcc, s86, v12
	s_and_b64 s[24:25], s[22:23], s[24:25]
	v_sub_u32_e32 v1, v1, v15
	s_and_b64 s[56:57], s[24:25], vcc
	v_add_u32_e32 v15, 1, v14
	v_cmp_le_u32_e32 vcc, s40, v1
	v_ashrrev_i32_e32 v0, 31, v4
	v_cmp_gt_i32_e64 s[24:25], s41, v4
	v_cndmask_b32_e32 v14, v14, v15, vcc
	v_subrev_u32_e32 v15, s40, v1
	v_cndmask_b32_e32 v1, v1, v15, vcc
	v_add_u32_e32 v15, 1, v14
	v_cmp_le_u32_e32 vcc, s40, v1
	v_mov_b32_e32 v47, 0x4140
	v_lshlrev_b32_e32 v52, 3, v2
	v_cndmask_b32_e32 v1, v14, v15, vcc
	v_xor_b32_e32 v1, v1, v0
	v_sub_u32_e32 v24, v1, v0
	v_mul_lo_u32 v0, v24, s40
	v_sub_u32_e32 v14, v4, v0
	v_lshlrev_b32_e32 v15, 3, v14
	v_add_u32_e32 v0, 0xfffffc00, v15
	v_mov_b32_e32 v1, v177
	v_lshl_add_u64 v[72:73], v[0:1], 1, s[74:75]
	v_sub_u32_e32 v1, 0, v6
	v_max_i32_e32 v1, v6, v1
	v_mul_hi_u32 v16, v1, v3
	v_cmp_gt_i32_e64 s[26:27], s81, v0
	v_mul_lo_u32 v17, v16, s40
	v_cmp_lt_i32_e32 vcc, s86, v14
	s_and_b64 s[26:27], s[24:25], s[26:27]
	v_sub_u32_e32 v1, v1, v17
	s_and_b64 s[58:59], s[26:27], vcc
	v_add_u32_e32 v17, 1, v16
	v_cmp_le_u32_e32 vcc, s40, v1
	v_ashrrev_i32_e32 v0, 31, v6
	v_cmp_gt_i32_e64 s[26:27], s41, v6
	v_cndmask_b32_e32 v16, v16, v17, vcc
	v_subrev_u32_e32 v17, s40, v1
	v_cndmask_b32_e32 v1, v1, v17, vcc
	v_add_u32_e32 v17, 1, v16
	v_cmp_le_u32_e32 vcc, s40, v1
	v_lshlrev_b32_e32 v38, 4, v2
	v_and_b32_e32 v2, 24, v15
	v_cndmask_b32_e32 v1, v16, v17, vcc
	v_xor_b32_e32 v1, v1, v0
	v_sub_u32_e32 v25, v1, v0
	v_mul_lo_u32 v0, v25, s40
	v_sub_u32_e32 v16, v6, v0
	v_lshlrev_b32_e32 v17, 3, v16
	v_add_u32_e32 v0, 0xfffffc00, v17
	v_mov_b32_e32 v1, v177
	v_lshl_add_u64 v[74:75], v[0:1], 1, s[74:75]
	v_sub_u32_e32 v1, 0, v8
	v_max_i32_e32 v1, v8, v1
	v_mul_hi_u32 v18, v1, v3
	v_cmp_gt_i32_e64 s[28:29], s81, v0
	v_mul_lo_u32 v19, v18, s40
	v_cmp_lt_i32_e32 vcc, s86, v16
	s_and_b64 s[28:29], s[26:27], s[28:29]
	v_sub_u32_e32 v1, v1, v19
	s_and_b64 s[62:63], s[28:29], vcc
	v_add_u32_e32 v19, 1, v18
	v_cmp_le_u32_e32 vcc, s40, v1
	v_ashrrev_i32_e32 v0, 31, v8
	v_cmp_gt_i32_e64 s[28:29], s41, v8
	v_cndmask_b32_e32 v18, v18, v19, vcc
; #define LAS __attribute__((address_space(3)))
; DI void hyena_unit(const Inputs& in, int l, unsigned char* ws, int half, int c, LAS unsigned char* lds, int tid) {
;     ...
;     { u32x4 fv[5], zv[8];
; #pragma unroll
;       for (int k = 0; k < 5; ++k) { const int i = tid + 512 * k, cp = i >= nfr, kk = cp ? i - nfr : i; fv[k] = (u32x4){0u, 0u, 0u, 0u};
;           if (i < 2 * nfr && kk < 2 * L / 8) fv[k] = *(const u32x4*)((cp ? FRO : FR) + kk * 8);
;           if (cp && kk == 2 * L / 8 - 1) fv[k].w &= 0xffffu; }
; #pragma unroll
;       for (int k = 0; k < 8; ++k) { const int i = tid + 512 * k, b = i / cpr, j = i % cpr, m = j * 8 - 1024; zv[k] = (u32x4){0u, 0u, 0u, 0u};
;           if (i < NB * cpr && m >= 0 && m < L) zv[k] = *(const u32x4*)(ZT + (size_t)(b * 512 + c) * L + m); }
; #pragma unroll
;       for (int k = 0; k < 5; ++k) { const int i = tid + 512 * k, cp = i >= nfr, kk = cp ? i - nfr : i; if (i < 2 * nfr) *(LAS u32x4*)(lds + cp * FRB + kk * 16) = fv[k]; }
; #pragma unroll
;       for (int k = 0; k < 8; ++k) { const int i = tid + 512 * k, b = i / cpr, j = i % cpr; if (i < NB * cpr) *(LAS u32x4*)(Zl + ((size_t)b * ZSP + (j >> 2) * 40 + (j & 3) * 8) * 2) = zv[k]; } }
	v_subrev_u32_e32 v19, s40, v1
	v_cndmask_b32_e32 v1, v1, v19, vcc
	v_add_u32_e32 v19, 1, v18
	v_cmp_le_u32_e32 vcc, s40, v1
	v_lshlrev_b32_e32 v56, 3, v5
	v_lshlrev_b32_e32 v40, 4, v5
	v_cndmask_b32_e32 v1, v18, v19, vcc
	v_xor_b32_e32 v1, v1, v0
	v_sub_u32_e32 v26, v1, v0
	v_mul_lo_u32 v0, v26, s40
	v_sub_u32_e32 v18, v8, v0
	v_lshlrev_b32_e32 v19, 3, v18
	v_add_u32_e32 v0, 0xfffffc00, v19
	v_mov_b32_e32 v1, v177
	v_lshl_add_u64 v[76:77], v[0:1], 1, s[74:75]
	v_sub_u32_e32 v1, 0, v10
	v_max_i32_e32 v1, v10, v1
	v_mul_hi_u32 v20, v1, v3
	v_cmp_gt_i32_e64 s[30:31], s81, v0
	v_mul_lo_u32 v21, v20, s40
	v_cmp_lt_i32_e32 vcc, s86, v18
	s_and_b64 s[30:31], s[28:29], s[30:31]
	v_sub_u32_e32 v1, v1, v21
	s_and_b64 s[94:95], s[30:31], vcc
	v_add_u32_e32 v21, 1, v20
	v_cmp_le_u32_e32 vcc, s40, v1
	v_ashrrev_i32_e32 v0, 31, v10
	v_cmp_gt_i32_e64 s[30:31], s41, v10
	v_cndmask_b32_e32 v20, v20, v21, vcc
	v_subrev_u32_e32 v21, s40, v1
	v_cndmask_b32_e32 v1, v1, v21, vcc
	v_add_u32_e32 v21, 1, v20
	v_cmp_le_u32_e32 vcc, s40, v1
	v_lshlrev_b32_e32 v60, 3, v7
	v_lshlrev_b32_e32 v42, 4, v7
	v_cndmask_b32_e32 v1, v20, v21, vcc
	v_xor_b32_e32 v1, v1, v0
	v_sub_u32_e32 v27, v1, v0
	v_mul_lo_u32 v0, v27, s40
	v_sub_u32_e32 v20, v10, v0
	v_lshlrev_b32_e32 v21, 3, v20
	v_add_u32_e32 v0, 0xfffffc00, v21
	v_mov_b32_e32 v1, v177
	v_lshl_add_u64 v[78:79], v[0:1], 1, s[74:75]
	v_add_u32_e32 v1, 0xa00, v182
	v_sub_u32_e32 v28, 0, v1
	v_max_i32_e32 v28, v1, v28
	v_mul_hi_u32 v29, v28, v3
	v_cmp_gt_i32_e64 s[34:35], s81, v0
	v_mul_lo_u32 v30, v29, s40
	v_cmp_lt_i32_e32 vcc, s86, v20
	s_and_b64 s[34:35], s[30:31], s[34:35]
	v_sub_u32_e32 v28, v28, v30
	s_and_b64 s[96:97], s[34:35], vcc
	v_add_u32_e32 v30, 1, v29
	v_cmp_le_u32_e32 vcc, s40, v28
	v_ashrrev_i32_e32 v0, 31, v1
	v_cmp_gt_i32_e64 s[34:35], s41, v1
	v_cndmask_b32_e32 v29, v29, v30, vcc
	v_subrev_u32_e32 v30, s40, v28
	v_cndmask_b32_e32 v28, v28, v30, vcc
	v_add_u32_e32 v30, 1, v29
	v_cmp_le_u32_e32 vcc, s40, v28
	v_lshlrev_b32_e32 v64, 3, v9
	v_lshlrev_b32_e32 v44, 4, v9
	v_cndmask_b32_e32 v28, v29, v30, vcc
	v_xor_b32_e32 v28, v28, v0
	v_sub_u32_e32 v28, v28, v0
	v_mul_lo_u32 v0, v28, s40
	v_sub_u32_e32 v29, v1, v0
	v_lshlrev_b32_e32 v30, 3, v29
	v_add_u32_e32 v0, 0xfffffc00, v30
	v_mov_b32_e32 v1, v177
	v_lshl_add_u64 v[80:81], v[0:1], 1, s[74:75]
	v_add_u32_e32 v1, 0xc00, v182
	v_sub_u32_e32 v31, 0, v1
	v_max_i32_e32 v31, v1, v31
	v_mul_hi_u32 v32, v31, v3
	v_cmp_gt_i32_e64 s[36:37], s81, v0
	v_mul_lo_u32 v33, v32, s40
	v_cmp_lt_i32_e32 vcc, s86, v29
	s_and_b64 s[36:37], s[34:35], s[36:37]
	v_sub_u32_e32 v31, v31, v33
	s_and_b64 s[64:65], s[36:37], vcc
	v_add_u32_e32 v33, 1, v32
	v_cmp_le_u32_e32 vcc, s40, v31
	v_ashrrev_i32_e32 v0, 31, v1
	v_cmp_gt_i32_e64 s[36:37], s41, v1
	v_cndmask_b32_e32 v32, v32, v33, vcc
	v_subrev_u32_e32 v33, s40, v31
	v_cndmask_b32_e32 v31, v31, v33, vcc
	v_add_u32_e32 v33, 1, v32
	v_cmp_le_u32_e32 vcc, s40, v31
	v_lshlrev_b32_e32 v68, 3, v11
	v_lshlrev_b32_e32 v46, 4, v11
	v_cndmask_b32_e32 v31, v32, v33, vcc
	v_xor_b32_e32 v31, v31, v0
	v_sub_u32_e32 v31, v31, v0
	v_mul_lo_u32 v0, v31, s40
	v_sub_u32_e32 v32, v1, v0
	v_lshlrev_b32_e32 v33, 3, v32
	v_add_u32_e32 v0, 0xfffffc00, v33
	v_mov_b32_e32 v1, v177
	v_lshl_add_u64 v[82:83], v[0:1], 1, s[74:75]
	v_add_u32_e32 v1, 0xe00, v182
	v_sub_u32_e32 v34, 0, v1
	v_max_i32_e32 v34, v1, v34
	v_mul_hi_u32 v3, v34, v3
	v_cmp_gt_i32_e64 s[38:39], s81, v0
	v_mul_lo_u32 v35, v3, s40
	v_cmp_lt_i32_e32 vcc, s86, v32
	s_and_b64 s[38:39], s[36:37], s[38:39]
	v_sub_u32_e32 v34, v34, v35
	s_and_b64 s[84:85], s[38:39], vcc
	v_add_u32_e32 v35, 1, v3
	v_cmp_le_u32_e32 vcc, s40, v34
	v_ashrrev_i32_e32 v0, 31, v1
	v_cmp_gt_i32_e64 s[38:39], s41, v1
	v_cndmask_b32_e32 v3, v3, v35, vcc
	v_subrev_u32_e32 v35, s40, v34
	v_cndmask_b32_e32 v34, v34, v35, vcc
	v_add_u32_e32 v35, 1, v3
	v_cmp_le_u32_e32 vcc, s40, v34
	s_mul_i32 s88, s83, 0x50
	v_ashrrev_i32_e32 v53, 31, v52
	v_cndmask_b32_e32 v3, v3, v35, vcc
	v_xor_b32_e32 v3, v3, v0
	v_sub_u32_e32 v34, v3, v0
	v_mul_lo_u32 v0, v34, s40
	v_sub_u32_e32 v35, v1, v0
	v_lshlrev_b32_e32 v36, 3, v35
	v_add_u32_e32 v0, 0xfffffc00, v36
	v_cmp_gt_i32_e64 s[40:41], s81, v0
	v_cmp_lt_i32_e32 vcc, s86, v35
	s_and_b64 s[40:41], s[38:39], s[40:41]
	s_and_b64 s[86:87], s[40:41], vcc
	v_mov_b32_e32 v1, v177
	v_cmp_gt_i32_e32 vcc, s42, v182
	v_lshl_add_u64 v[84:85], v[0:1], 1, s[74:75]
	v_lshrrev_b32_e32 v1, 2, v12
	v_cndmask_b32_e64 v0, v47, 0, vcc
	v_cmp_gt_i32_e32 vcc, s42, v4
	v_add_u32_e32 v37, 0, v0
	v_and_b32_e32 v4, 24, v17
	v_cndmask_b32_e64 v0, v47, 0, vcc
	v_cmp_gt_i32_e32 vcc, s42, v6
	v_add_u32_e32 v39, 0, v0
	v_and_b32_e32 v6, 24, v19
	v_cndmask_b32_e64 v0, v47, 0, vcc
	v_cmp_gt_i32_e32 vcc, s42, v8
	v_add_u32_e32 v41, 0, v0
	s_lshr_b32 s74, s81, 10
	v_cndmask_b32_e64 v0, v47, 0, vcc
	v_cmp_gt_i32_e32 vcc, s42, v10
	v_add_u32_e32 v43, 0, v0
	v_and_b32_e32 v8, 24, v21
	v_cndmask_b32_e64 v0, v47, 0, vcc
	v_add_u32_e32 v45, 0, v0
	v_and_b32_e32 v0, 24, v13
	v_mad_u64_u32 v[0:1], s[40:41], v1, 40, v[0:1]
	v_lshrrev_b32_e32 v1, 2, v14
	v_mad_u64_u32 v[2:3], s[40:41], v1, 40, v[2:3]
	v_lshrrev_b32_e32 v1, 2, v16
	v_mad_u64_u32 v[4:5], s[40:41], v1, 40, v[4:5]
	v_lshrrev_b32_e32 v1, 2, v18
	v_mad_u64_u32 v[6:7], s[40:41], v1, 40, v[6:7]
	v_lshrrev_b32_e32 v1, 2, v20
	v_cvt_f32_u32_e32 v3, s74
	v_mad_u64_u32 v[8:9], s[40:41], v1, 40, v[8:9]
	v_lshrrev_b32_e32 v1, 2, v29
	v_and_b32_e32 v10, 24, v30
	v_mad_u64_u32 v[10:11], s[40:41], v1, 40, v[10:11]
	v_lshrrev_b32_e32 v1, 2, v32
	v_and_b32_e32 v12, 24, v33
	v_mad_u64_u32 v[12:13], s[40:41], v1, 40, v[12:13]
	v_lshrrev_b32_e32 v1, 2, v35
	v_and_b32_e32 v14, 24, v36
; #define LAS __attribute__((address_space(3)))
; DI void hyena_unit(const Inputs& in, int l, unsigned char* ws, int half, int c, LAS unsigned char* lds, int tid) {
;     ...
;     const int wave = tid >> 6, lane = tid & 63, i32 = lane & 31, g = lane >> 5;
;     const int gpb = nblk / 32, a0 = 32 * (wave % gpb), b0 = 2 * (wave / gpb);
;     const int dlo = a0 - nblk + 1, dhi = a0 + 31;
;     f32x16 acc0 = {}, acc1 = {};
;     const LAS unsigned char* Zb = Zl + (size_t)b0 * ZSP * 2;
;     const int zstep = ZSP * 2;
;     int s0 = L - 32 * dlo - i32 + 8 * g;
;     const LAS unsigned char* zp0 = Zb + ((32 + a0 + i32 - dlo) * 40 + 8 * g) * 2;
	v_mad_u64_u32 v[14:15], s[40:41], v1, 40, v[14:15]
	v_rcp_iflag_f32_e32 v1, v3
	s_sub_i32 s40, 0, s74
	v_ashrrev_i32_e32 v3, 6, v182
	v_sub_u32_e32 v9, 0, v3
	v_mul_f32_e32 v1, 0x4f7ffffe, v1
	v_cvt_u32_f32_e32 v1, v1
	v_max_i32_e32 v9, v3, v9
	v_and_b32_e32 v5, 31, v182
	v_bfe_u32 v7, v182, 5, 1
	v_mul_lo_u32 v11, s40, v1
	v_mul_hi_u32 v11, v1, v11
	v_add_u32_e32 v1, v1, v11
	v_mul_hi_u32 v1, v9, v1
	v_mul_lo_u32 v11, v1, s74
	v_sub_u32_e32 v9, v9, v11
	v_add_u32_e32 v11, 1, v1
	v_cmp_le_u32_e32 vcc, s74, v9
	s_mul_i32 s40, s83, 0xa0
	s_mul_i32 s42, s83, 40
	v_cndmask_b32_e32 v1, v1, v11, vcc
	v_subrev_u32_e32 v11, s74, v9
	v_cndmask_b32_e32 v9, v9, v11, vcc
	v_add_u32_e32 v11, 1, v1
	v_cmp_le_u32_e32 vcc, s74, v9
	v_mov_b32_e32 v17, v177
	v_mov_b32_e32 v55, v177
	v_cndmask_b32_e32 v1, v1, v11, vcc
	v_xor_b32_e32 v1, v1, v22
	v_sub_u32_e32 v9, v1, v22
	v_mul_lo_u32 v11, v9, s74
	v_sub_u32_e32 v13, v3, v11
	v_lshlrev_b32_e32 v13, 5, v13
	v_subrev_u32_e32 v15, s89, v13
	v_or_b32_e32 v16, 31, v13
	v_mul_lo_u32 v29, s40, v9
	v_cmp_lt_i32_e64 s[40:41], v15, v16
	v_and_b32_e32 v15, 1, v182
	v_cmp_eq_u32_e32 vcc, 1, v15
	v_or_b32_e32 v13, v13, v5
	v_lshlrev_b32_e32 v92, 10, v9
	v_cndmask_b32_e32 v15, 0, v47, vcc
	v_add_u32_e32 v91, 0, v15
	v_lshlrev_b32_e32 v15, 2, v7
	v_mul_lo_u32 v9, v13, 40
	v_lshlrev_b32_e32 v18, 5, v13
	v_or_b32_e32 v9, v9, v15
	v_mov_b32_e32 v13, 0xa00
	v_lshl_add_u32 v94, v9, 1, v13
	v_mul_lo_u32 v13, v23, s42
	v_lshlrev_b32_e32 v16, 3, v7
	v_add_lshl_u32 v0, v0, v13, 1
	v_mul_lo_u32 v13, v24, s42
	s_add_u32 s74, s92, 0x1cd00000
	v_add_lshl_u32 v2, v2, v13, 1
	v_mul_lo_u32 v13, v25, s42
	v_lshl_or_b32 v11, v11, 10, v16
	s_addc_u32 s75, s93, 0
	v_ashrrev_i32_e32 v19, 31, v18
	v_add_lshl_u32 v4, v4, v13, 1
	v_mul_lo_u32 v13, v26, s42
	v_lshl_add_u32 v11, s81, 1, v11
	v_lshl_add_u64 v[20:21], v[18:19], 1, s[74:75]
	v_or_b32_e32 v18, v18, v15
	v_add_lshl_u32 v6, v6, v13, 1
	v_mul_lo_u32 v13, v27, s42
	v_sub_u32_e32 v11, v11, v5
	v_lshlrev_b32_e32 v3, 10, v3
	v_ashrrev_i32_e32 v19, 31, v18
	v_add_lshl_u32 v8, v8, v13, 1
	v_mul_lo_u32 v13, v28, s42
	v_sub_u32_e32 v3, v11, v3
	v_add_lshl_u32 v10, v10, v13, 1
	v_mul_lo_u32 v13, v31, s42
	v_lshl_add_u64 v[88:89], v[18:19], 1, s[74:75]
	v_add_u32_e32 v103, -16, v3
	v_add_u32_e32 v3, s89, v5
	s_movk_i32 s74, 0x50
	v_add_lshl_u32 v12, v12, v13, 1
	v_mul_lo_u32 v13, v34, s42
	v_mad_u32_u24 v5, v3, s74, v29
	v_lshlrev_b32_e32 v7, 4, v7
	v_readlane_b32 s75, v255, 6
	s_movk_i32 s42, 0xa0
	v_mul_lo_u32 v1, v1, s42
	v_add3_u32 v104, v5, v7, s75
	v_mul_i32_i24_e32 v5, 0xa0, v22
	v_sub_u32_e32 v1, v1, v5
	v_add_u32_e32 v1, 0x50, v1
	v_add_u32_e32 v90, 0, v29
	v_mul_lo_u32 v1, s83, v1
	v_add_u32_e32 v9, s88, v90
	v_add_lshl_u32 v13, v14, v13, 1
	v_mad_u32_u24 v1, v3, s74, v1
	s_mul_i32 s81, s89, 0x50
	v_ashrrev_i32_e32 v57, 31, v56
	v_mov_b32_e32 v59, v177
	v_ashrrev_i32_e32 v61, 31, v60
	v_mov_b32_e32 v63, v177
	v_ashrrev_i32_e32 v65, 31, v64
	v_mov_b32_e32 v67, v177
	v_ashrrev_i32_e32 v69, 31, v68
	v_lshl_add_u64 v[86:87], v[20:21], 0, v[16:17]
	v_or_b32_e32 v93, 0x200, v92
	v_lshlrev_b32_e32 v95, 9, v23
	v_lshlrev_b32_e32 v96, 9, v24
	v_lshlrev_b32_e32 v97, 9, v25
	v_lshlrev_b32_e32 v98, 9, v26
	v_lshlrev_b32_e32 v99, 9, v27
	v_lshlrev_b32_e32 v100, 9, v28
	v_lshlrev_b32_e32 v101, 9, v31
	v_lshlrev_b32_e32 v102, 9, v34
	v_add3_u32 v105, v1, v7, s75
	s_addk_i32 s81, 0x9b0
	v_add_u32_e32 v106, v37, v38
	v_add_u32_e32 v107, v39, v40
	v_add_u32_e32 v108, v41, v42
	v_add_u32_e32 v109, v43, v44
	v_add_u32_e32 v110, v45, v46
	v_add_u32_e32 v111, 0, v0
	v_add_u32_e32 v112, 0, v2
	v_add_u32_e32 v113, 0, v4
	v_add_u32_e32 v114, 0, v6
	v_add_u32_e32 v115, 0, v8
	v_add_u32_e32 v116, 0, v10
	v_add_u32_e32 v117, 0, v12
	v_add_u32_e32 v118, 0, v13
	v_add_u32_e32 v119, v9, v94
	s_branch .LBB0_618
; #define LAS __attribute__((address_space(3)))
; DI unsigned cvt_pk_bf16(float lo, float hi) { const f32x2 v = {lo, hi}; return __builtin_bit_cast(unsigned, __builtin_convertvector(v, bf16x2_t)); }
; DI float bflo(unsigned w) { return __uint_as_float(w << 16); }
; DI float bfhi(unsigned w) { return __uint_as_float(w & 0xffff0000u); }
; DI void hyena_unit(const Inputs& in, int l, unsigned char* ws, int half, int c, LAS unsigned char* lds, int tid) {
;     ...
;     const float bias = in.hy_bias[l * 512 + c];
;     u32x2 xx[2][4];
; #pragma unroll
;     for (int k = 0; k < 2; ++k)
; #pragma unroll
;         for (int q = 0; q < 4; ++q) xx[k][q] = *(const u32x2*)(XT + (size_t)((b0 + k) * 512 + c) * L + 32 * (a0 + i32) + 8 * q + 4 * g);
; #pragma unroll
;     for (int k = 0; k < 2; ++k) {
;         const int a = a0 + i32, b = b0 + k;
; #pragma unroll
;         for (int q = 0; q < 4; ++q) {
;             const int t0 = 32 * a + 8 * q + 4 * g;
;             const u32x2 zz = *(const LAS u32x2*)(Zb + k * zstep + ((32 + a) * 40 + 8 * q + 4 * g) * 2);
;             bf16_t* xp = XT + (size_t)(b * 512 + c) * L + t0;
;             const float z0 = bflo(zz.x), z1 = bfhi(zz.x), z2 = bflo(zz.y), z3 = bfhi(zz.y);
;             const float x0 = bflo(xx[k][q].x), x1 = bfhi(xx[k][q].x), x2 = bflo(xx[k][q].y), x3 = bfhi(xx[k][q].y);
;             const float c0 = k ? acc1[4 * q + 0] : acc0[4 * q + 0], c1 = k ? acc1[4 * q + 1] : acc0[4 * q + 1], c2 = k ? acc1[4 * q + 2] : acc0[4 * q + 2], c3 = k ? acc1[4 * q + 3] : acc0[4 * q + 3];
;             u32x2 o; o.x = cvt_pk_bf16((c0 + z0 * bias) * x0, (c1 + z1 * bias) * x1); o.y = cvt_pk_bf16((c2 + z2 * bias) * x2, (c3 + z3 * bias) * x3);
;             *(u32x2*)xp = o;
;         }
;     }
;     __syncthreads();
.LBB0_617:
	s_or_b64 exec, exec, vcc
	v_readlane_b32 s42, v255, 13
	s_add_i32 s74, s79, s42
	s_ashr_i32 s75, s74, 31
	s_lshl_b64 s[74:75], s[74:75], 2
	s_add_u32 s74, s60, s74
	v_add_u32_e32 v34, s79, v92
	s_addc_u32 s75, s61, s75
	v_ashrrev_i32_e32 v35, 31, v34
	global_load_dword v32, v177, s[74:75]
	v_lshlrev_b64 v[34:35], s33, v[34:35]
	v_lshlrev_b64 v[44:45], 1, v[34:35]
	v_lshl_add_u64 v[34:35], v[86:87], 0, v[44:45]
	global_load_dwordx2 v[120:121], v[34:35], off
	global_load_dwordx2 v[122:123], v[34:35], off offset:16
	global_load_dwordx2 v[124:125], v[34:35], off offset:32
	global_load_dwordx2 v[126:127], v[34:35], off offset:48
	v_add_u32_e32 v34, s79, v93
	v_ashrrev_i32_e32 v35, 31, v34
	v_lshlrev_b64 v[34:35], s33, v[34:35]
	v_lshlrev_b64 v[42:43], 1, v[34:35]
	v_lshl_add_u64 v[34:35], v[86:87], 0, v[42:43]
	global_load_dwordx2 v[40:41], v[34:35], off
	global_load_dwordx2 v[38:39], v[34:35], off offset:16
	global_load_dwordx2 v[36:37], v[34:35], off offset:32
	s_nop 0
	global_load_dwordx2 v[34:35], v[34:35], off offset:48
	v_add_u32_e32 v33, v90, v94
	v_add_u32_e32 v33, 0x8080, v33
	v_lshl_add_u64 v[128:129], v[88:89], 0, v[44:45]
	ds_read2_b64 v[44:47], v33 offset0:64 offset1:66
	ds_read2_b64 v[48:51], v33 offset0:68 offset1:70
	s_add_i32 s79, s79, s71
	s_cmpk_lt_i32 s79, 0x200
	s_waitcnt lgkmcnt(1)
	v_lshlrev_b32_e32 v130, 16, v44
	v_and_b32_e32 v131, 0xffff0000, v44
	v_lshlrev_b32_e32 v44, 16, v45
	v_and_b32_e32 v45, 0xffff0000, v45
	s_waitcnt vmcnt(8)
	v_pk_fma_f32 v[16:17], v[32:33], v[130:131], v[16:17] op_sel_hi:[0,1,1]
	s_waitcnt vmcnt(7)
	v_lshlrev_b32_e32 v132, 16, v120
	v_and_b32_e32 v133, 0xffff0000, v120
	v_lshlrev_b32_e32 v120, 16, v121
	v_and_b32_e32 v121, 0xffff0000, v121
	v_pk_fma_f32 v[18:19], v[32:33], v[44:45], v[18:19] op_sel_hi:[0,1,1]
	v_pk_mul_f32 v[16:17], v[16:17], v[132:133]
	v_pk_mul_f32 v[18:19], v[18:19], v[120:121]
	v_cvt_pk_bf16_f32 v16, v16, v17
	v_cvt_pk_bf16_f32 v17, v18, v19
	global_store_dwordx2 v[128:129], v[16:17], off
	v_lshlrev_b32_e32 v16, 16, v46
	v_and_b32_e32 v17, 0xffff0000, v46
	s_waitcnt vmcnt(7)
	v_lshlrev_b32_e32 v18, 16, v122
	v_and_b32_e32 v19, 0xffff0000, v122
	v_pk_fma_f32 v[16:17], v[32:33], v[16:17], v[20:21] op_sel_hi:[0,1,1]
	v_pk_mul_f32 v[16:17], v[16:17], v[18:19]
	v_lshlrev_b32_e32 v18, 16, v47
	v_and_b32_e32 v19, 0xffff0000, v47
	v_lshlrev_b32_e32 v20, 16, v123
	v_and_b32_e32 v21, 0xffff0000, v123
	v_pk_fma_f32 v[18:19], v[32:33], v[18:19], v[22:23] op_sel_hi:[0,1,1]
	v_pk_mul_f32 v[18:19], v[18:19], v[20:21]
	v_cvt_pk_bf16_f32 v16, v16, v17
	v_cvt_pk_bf16_f32 v17, v18, v19
	global_store_dwordx2 v[128:129], v[16:17], off offset:16
	s_waitcnt lgkmcnt(0)
	v_lshlrev_b32_e32 v16, 16, v48
	v_and_b32_e32 v17, 0xffff0000, v48
	s_waitcnt vmcnt(7)
	v_lshlrev_b32_e32 v18, 16, v124
	v_and_b32_e32 v19, 0xffff0000, v124
	v_pk_fma_f32 v[16:17], v[32:33], v[16:17], v[24:25] op_sel_hi:[0,1,1]
	v_pk_mul_f32 v[16:17], v[16:17], v[18:19]
	v_lshlrev_b32_e32 v18, 16, v49
	v_and_b32_e32 v19, 0xffff0000, v49
	v_lshlrev_b32_e32 v20, 16, v125
	v_and_b32_e32 v21, 0xffff0000, v125
	v_pk_fma_f32 v[18:19], v[32:33], v[18:19], v[26:27] op_sel_hi:[0,1,1]
	v_pk_mul_f32 v[18:19], v[18:19], v[20:21]
	v_cvt_pk_bf16_f32 v16, v16, v17
	v_cvt_pk_bf16_f32 v17, v18, v19
	global_store_dwordx2 v[128:129], v[16:17], off offset:32
	v_lshlrev_b32_e32 v16, 16, v50
	v_and_b32_e32 v17, 0xffff0000, v50
	s_waitcnt vmcnt(7)
	v_lshlrev_b32_e32 v18, 16, v126
	v_and_b32_e32 v19, 0xffff0000, v126
	v_pk_fma_f32 v[16:17], v[32:33], v[16:17], v[28:29] op_sel_hi:[0,1,1]
	v_pk_mul_f32 v[16:17], v[16:17], v[18:19]
	v_lshlrev_b32_e32 v18, 16, v51
	v_and_b32_e32 v19, 0xffff0000, v51
	v_lshlrev_b32_e32 v20, 16, v127
	v_and_b32_e32 v21, 0xffff0000, v127
	v_pk_fma_f32 v[18:19], v[32:33], v[18:19], v[30:31] op_sel_hi:[0,1,1]
	v_pk_mul_f32 v[18:19], v[18:19], v[20:21]
	v_cvt_pk_bf16_f32 v16, v16, v17
	v_cvt_pk_bf16_f32 v17, v18, v19
	v_add_u32_e32 v26, 0x8080, v119
	global_store_dwordx2 v[128:129], v[16:17], off offset:48
	ds_read2_b64 v[16:19], v26 offset0:64 offset1:66
	s_waitcnt vmcnt(7)
	v_lshlrev_b32_e32 v24, 16, v40
	v_and_b32_e32 v25, 0xffff0000, v40
	v_lshl_add_u64 v[20:21], v[88:89], 0, v[42:43]
	s_waitcnt lgkmcnt(0)
	v_lshlrev_b32_e32 v22, 16, v16
	v_and_b32_e32 v23, 0xffff0000, v16
	v_lshlrev_b32_e32 v16, 16, v17
	v_and_b32_e32 v17, 0xffff0000, v17
	v_pk_fma_f32 v[0:1], v[32:33], v[22:23], v[0:1] op_sel_hi:[0,1,1]
	v_lshlrev_b32_e32 v22, 16, v41
	v_and_b32_e32 v23, 0xffff0000, v41
	v_pk_fma_f32 v[2:3], v[32:33], v[16:17], v[2:3] op_sel_hi:[0,1,1]
	v_pk_mul_f32 v[0:1], v[0:1], v[24:25]
	v_pk_mul_f32 v[2:3], v[2:3], v[22:23]
	v_cvt_pk_bf16_f32 v0, v0, v1
	v_cvt_pk_bf16_f32 v1, v2, v3
	global_store_dwordx2 v[20:21], v[0:1], off
	v_lshlrev_b32_e32 v0, 16, v18
	v_and_b32_e32 v1, 0xffff0000, v18
	s_waitcnt vmcnt(7)
	v_lshlrev_b32_e32 v2, 16, v38
	v_and_b32_e32 v3, 0xffff0000, v38
	v_pk_fma_f32 v[0:1], v[32:33], v[0:1], v[4:5] op_sel_hi:[0,1,1]
	v_pk_mul_f32 v[0:1], v[0:1], v[2:3]
	v_lshlrev_b32_e32 v2, 16, v19
	v_and_b32_e32 v3, 0xffff0000, v19
	v_lshlrev_b32_e32 v4, 16, v39
	v_and_b32_e32 v5, 0xffff0000, v39
	v_pk_fma_f32 v[2:3], v[32:33], v[2:3], v[6:7] op_sel_hi:[0,1,1]
	v_pk_mul_f32 v[2:3], v[2:3], v[4:5]
	v_cvt_pk_bf16_f32 v0, v0, v1
	v_cvt_pk_bf16_f32 v1, v2, v3
	global_store_dwordx2 v[20:21], v[0:1], off offset:16
	ds_read2_b64 v[0:3], v26 offset0:68 offset1:70
	s_waitcnt vmcnt(7)
	v_lshlrev_b32_e32 v6, 16, v36
	v_and_b32_e32 v7, 0xffff0000, v36
	s_waitcnt lgkmcnt(0)
	v_lshlrev_b32_e32 v4, 16, v0
	v_and_b32_e32 v5, 0xffff0000, v0
	v_pk_fma_f32 v[4:5], v[32:33], v[4:5], v[8:9] op_sel_hi:[0,1,1]
	v_pk_mul_f32 v[4:5], v[4:5], v[6:7]
	v_lshlrev_b32_e32 v6, 16, v37
	v_cvt_pk_bf16_f32 v0, v4, v5
	v_lshlrev_b32_e32 v4, 16, v1
	v_and_b32_e32 v5, 0xffff0000, v1
	v_and_b32_e32 v7, 0xffff0000, v37
	v_pk_fma_f32 v[4:5], v[32:33], v[4:5], v[10:11] op_sel_hi:[0,1,1]
	v_pk_mul_f32 v[4:5], v[4:5], v[6:7]
	s_nop 0
	v_cvt_pk_bf16_f32 v1, v4, v5
	v_lshlrev_b32_e32 v4, 16, v2
	v_and_b32_e32 v5, 0xffff0000, v2
	global_store_dwordx2 v[20:21], v[0:1], off offset:32
	s_waitcnt vmcnt(7)
	v_lshlrev_b32_e32 v0, 16, v34
	v_and_b32_e32 v1, 0xffff0000, v34
	v_pk_fma_f32 v[4:5], v[32:33], v[4:5], v[12:13] op_sel_hi:[0,1,1]
	v_lshlrev_b32_e32 v2, 16, v3
	v_and_b32_e32 v3, 0xffff0000, v3
	v_pk_mul_f32 v[0:1], v[4:5], v[0:1]
	v_lshlrev_b32_e32 v4, 16, v35
	v_and_b32_e32 v5, 0xffff0000, v35
	v_pk_fma_f32 v[2:3], v[32:33], v[2:3], v[14:15] op_sel_hi:[0,1,1]
	v_pk_mul_f32 v[2:3], v[2:3], v[4:5]
	v_cvt_pk_bf16_f32 v0, v0, v1
	v_cvt_pk_bf16_f32 v1, v2, v3
	global_store_dwordx2 v[20:21], v[0:1], off offset:48
	s_barrier
	s_cbranch_scc0 .LBB0_673

; #define LAS __attribute__((address_space(3)))
; DI void hyena_unit(const Inputs& in, int l, unsigned char* ws, int half, int c, LAS unsigned char* lds, int tid) {
;     ...
;       for (int k = 0; k < 8; ++k) { const int i = tid + 512 * k, b = i / cpr, j = i % cpr; if (i < NB * cpr) *(LAS u32x4*)(Zl + ((size_t)b * ZSP + (j >> 2) * 40 + (j & 3) * 8) * 2) = zv[k]; } }
.LBB0_657:
	ds_write_b128 v118, v[44:47] offset:33408

; #define LAS __attribute__((address_space(3)))
; DI void hyena_unit(const Inputs& in, int l, unsigned char* ws, int half, int c, LAS unsigned char* lds, int tid) {
;     ...
;       for (int k = 0; k < 8; ++k) { const int i = tid + 512 * k, b = i / cpr, j = i % cpr; if (i < NB * cpr) *(LAS u32x4*)(Zl + ((size_t)b * ZSP + (j >> 2) * 40 + (j & 3) * 8) * 2) = zv[k]; } }
.LBB0_666:
	ds_write_b128 v111, v[24:27] offset:33408
	s_or_b64 exec, exec, s[74:75]
	s_and_saveexec_b64 s[74:75], s[24:25]
	s_cbranch_execz .LBB0_651
.LBB0_667:
	ds_write_b128 v112, v[16:19] offset:33408
	s_or_b64 exec, exec, s[74:75]
	s_and_saveexec_b64 s[74:75], s[26:27]
	s_cbranch_execz .LBB0_652
.LBB0_668:
	ds_write_b128 v113, v[32:35] offset:33408
	s_or_b64 exec, exec, s[74:75]
	s_and_saveexec_b64 s[74:75], s[28:29]
	s_cbranch_execz .LBB0_653
.LBB0_669:
	ds_write_b128 v114, v[28:31] offset:33408
	s_or_b64 exec, exec, s[74:75]
	s_and_saveexec_b64 s[74:75], s[30:31]
	s_cbranch_execz .LBB0_654
.LBB0_670:
	ds_write_b128 v115, v[40:43] offset:33408
	s_or_b64 exec, exec, s[74:75]
	s_and_saveexec_b64 s[74:75], s[34:35]
	s_cbranch_execz .LBB0_655
.LBB0_671:
	ds_write_b128 v116, v[36:39] offset:33408
	s_or_b64 exec, exec, s[74:75]
	s_and_saveexec_b64 s[74:75], s[36:37]
	s_cbranch_execz .LBB0_656
.LBB0_672:
	ds_write_b128 v117, v[48:51] offset:33408
	s_or_b64 exec, exec, s[74:75]
	s_and_saveexec_b64 s[74:75], s[38:39]
	s_cbranch_execnz .LBB0_657
	s_branch .LBB0_658
